# v26 plus hand-written in-proj non-head epilogue (modulo-scheduled sigmoid/silu, per-class paths)
# speedup vs baseline: 1.0068x; 1.0000x over previous
; DI u32x4 pack8(const float* x) { u32x4 v; v.x = cvt_pk(x[0], x[1]); v.y = cvt_pk(x[2], x[3]); v.z = cvt_pk(x[4], x[5]); v.w = cvt_pk(x[6], x[7]); return v; }
; DI float sigmoidf_(float v) { return __builtin_amdgcn_rcpf(1.0f + __expf(-v)); }
;     DI void operator()(const f32x4 (&acc)[2][2][4][2], const Unit& u, int wr, int wc, int fr, int fq) const {
;     ...
; #pragma unroll
;         for (int bj = 0; bj < 2; ++bj) {
;             const int colw = u.pn * BM + bj * HALF + wc * 32;
;             const int act = colw < C_SILU ? 0 : (colw < C_GATE ? 1 : 2);
; #pragma unroll
;             for (int ai = 0; ai < 2; ++ai)
; #pragma unroll
;                 for (int m = 0; m < 4; ++m) {
;                     float v[8];
; #pragma unroll
;                     for (int j = 0; j < 4; ++j) { v[j] = acc[ai][bj][m][0][j] * rstd[ai][m]; v[4 + j] = acc[ai][bj][m][1][j] * rstd[ai][m]; }
;                     if (act) {
; #pragma unroll
;                         for (int j = 0; j < 8; ++j) { const float sg = sigmoidf_(v[j]); v[j] = act == 1 ? v[j] * sg : sg; }
;                     }
;                     *(u32x4*)(O + (size_t)(row0 + ai * HALF + m * 16) * LDP + col0 + bj * HALF) = pack8(v);
;                 }
.LBB0_133:
	s_lshl_b32 s4, s10, 8
	v_lshl_add_u32 v170, s2, 8, v147
	v_or_b32_e32 v130, s4, v197
	s_mov_b64 s[2:3], -1
	v_ashrrev_i32_e32 v171, 31, v170
	v_lshl_add_u64 v[132:133], v[170:171], 2, s[58:59]
	v_add_u32_e32 v222, 16, v170
	v_add_u32_e32 v211, 32, v170
	v_add_u32_e32 v209, 48, v170
	v_add_u32_e32 v207, 0x80, v170
	v_add_u32_e32 v205, 0x90, v170
	v_add_u32_e32 v203, 0xa0, v170
	v_add_u32_e32 v201, 0xb0, v170
	v_ashrrev_i32_e32 v223, 31, v222
	v_ashrrev_i32_e32 v221, 31, v211
	v_ashrrev_i32_e32 v210, 31, v209
	v_ashrrev_i32_e32 v208, 31, v207
	v_ashrrev_i32_e32 v206, 31, v205
	v_ashrrev_i32_e32 v204, 31, v203
	v_ashrrev_i32_e32 v202, 31, v201
	s_cmp_lt_i32 s10, 19
	v_fmamk_f32 v172, v238, 0x3a000000, v218
	v_cmp_gt_f32_e32 vcc, s33, v172
	v_mul_f32_e32 v131, 0x4b800000, v172
	s_nop 0
	v_cndmask_b32_e32 v172, v172, v131, vcc
	v_rsq_f32_e32 v172, v172
	s_nop 0
	v_mul_f32_e32 v131, 0x45800000, v172
	v_cndmask_b32_e32 v172, v172, v131, vcc
	v_fmamk_f32 v168, v239, 0x3a000000, v218
	v_cmp_gt_f32_e32 vcc, s33, v168
	v_mul_f32_e32 v131, 0x4b800000, v168
	s_nop 0
	v_cndmask_b32_e32 v168, v168, v131, vcc
	v_rsq_f32_e32 v168, v168
	s_nop 0
	v_mul_f32_e32 v131, 0x45800000, v168
	v_cndmask_b32_e32 v168, v168, v131, vcc
	v_fmamk_f32 v166, v240, 0x3a000000, v218
	v_cmp_gt_f32_e32 vcc, s33, v166
	v_mul_f32_e32 v131, 0x4b800000, v166
	s_nop 0
	v_cndmask_b32_e32 v166, v166, v131, vcc
	v_rsq_f32_e32 v166, v166
	s_nop 0
	v_mul_f32_e32 v131, 0x45800000, v166
	v_cndmask_b32_e32 v166, v166, v131, vcc
	v_fmamk_f32 v164, v241, 0x3a000000, v218
	v_cmp_gt_f32_e32 vcc, s33, v164
	v_mul_f32_e32 v131, 0x4b800000, v164
	s_nop 0
	v_cndmask_b32_e32 v164, v164, v131, vcc
	v_rsq_f32_e32 v164, v164
	s_nop 0
	v_mul_f32_e32 v131, 0x45800000, v164
	v_cndmask_b32_e32 v164, v164, v131, vcc
	v_fmamk_f32 v162, v242, 0x3a000000, v218
	v_cmp_gt_f32_e32 vcc, s33, v162
	v_mul_f32_e32 v131, 0x4b800000, v162
	s_nop 0
	v_cndmask_b32_e32 v162, v162, v131, vcc
	v_rsq_f32_e32 v162, v162
	s_nop 0
	v_mul_f32_e32 v131, 0x45800000, v162
	v_cndmask_b32_e32 v162, v162, v131, vcc
	v_fmamk_f32 v160, v243, 0x3a000000, v218
	v_cmp_gt_f32_e32 vcc, s33, v160
	v_mul_f32_e32 v131, 0x4b800000, v160
	s_nop 0
	v_cndmask_b32_e32 v160, v160, v131, vcc
	v_rsq_f32_e32 v160, v160
	s_nop 0
	v_mul_f32_e32 v131, 0x45800000, v160
	v_cndmask_b32_e32 v160, v160, v131, vcc
	v_fmamk_f32 v158, v244, 0x3a000000, v218
	v_cmp_gt_f32_e32 vcc, s33, v158
	v_mul_f32_e32 v131, 0x4b800000, v158
	s_nop 0
	v_cndmask_b32_e32 v158, v158, v131, vcc
	v_rsq_f32_e32 v158, v158
	s_nop 0
	v_mul_f32_e32 v131, 0x45800000, v158
	v_cndmask_b32_e32 v158, v158, v131, vcc
	v_fmamk_f32 v128, v245, 0x3a000000, v218
	v_cmp_gt_f32_e32 vcc, s33, v128
	v_mul_f32_e32 v131, 0x4b800000, v128
	s_nop 0
	v_cndmask_b32_e32 v128, v128, v131, vcc
	v_rsq_f32_e32 v128, v128
	s_nop 0
	v_mul_f32_e32 v131, 0x45800000, v128
	v_cndmask_b32_e32 v156, v128, v131, vcc
	s_cbranch_scc1 .LBB0_199
	s_or_b32 s8, s4, s83
	s_mov_b32 s5, 0xbfb8aa3b
	s_mov_b32 s6, 0x8c000
	s_mov_b32 s7, 0
	s_mov_b32 s2, 0x2bc000
	s_mov_b32 s3, 0
	v_mov_b64_e32 v[132:133], s[56:57]
	v_mad_i64_i32 v[132:133], vcc, v170, s68, v[132:133]
	v_mov_b32_e32 v131, 0
	v_lshl_add_u64 v[132:133], v[130:131], 1, v[132:133]
	v_mov_b64_e32 v[134:135], v[132:133]
	s_cmpk_lt_i32 s8, 0x1da0
	s_cbranch_scc1 .Lp2e_b0_act0
	s_cmpk_lt_i32 s8, 0x25a0
	s_cbranch_scc1 .Lp2e_b0_act1
	v_mul_f32_e32 v176, v124, v172
	v_mul_f32_e32 v176, s5, v176
	v_mul_f32_e32 v177, v125, v172
	v_exp_f32_e32 v176, v176
	v_mul_f32_e32 v177, s5, v177
	v_add_f32_e32 v176, 1.0, v176
	v_mul_f32_e32 v178, v126, v172
	v_exp_f32_e32 v177, v177
	v_mul_f32_e32 v178, s5, v178
	v_rcp_f32_e32 v176, v176
	v_add_f32_e32 v177, 1.0, v177
	v_mul_f32_e32 v179, v127, v172
	v_exp_f32_e32 v178, v178
	v_mul_f32_e32 v179, s5, v179
	v_rcp_f32_e32 v177, v177
	v_add_f32_e32 v178, 1.0, v178
	v_mul_f32_e32 v180, v120, v172
	v_exp_f32_e32 v179, v179
	v_mul_f32_e32 v180, s5, v180
	v_rcp_f32_e32 v178, v178
	v_add_f32_e32 v179, 1.0, v179
	v_mul_f32_e32 v181, v121, v172
	v_exp_f32_e32 v180, v180
	v_mul_f32_e32 v181, s5, v181
	v_rcp_f32_e32 v179, v179
	v_add_f32_e32 v180, 1.0, v180
	v_mul_f32_e32 v182, v122, v172
	v_exp_f32_e32 v181, v181
	v_mul_f32_e32 v182, s5, v182
	v_rcp_f32_e32 v180, v180
	v_add_f32_e32 v181, 1.0, v181
	v_mul_f32_e32 v183, v123, v172
	v_exp_f32_e32 v182, v182
	v_mul_f32_e32 v183, s5, v183
	v_rcp_f32_e32 v181, v181
	v_add_f32_e32 v182, 1.0, v182
	v_mul_f32_e32 v202, v108, v168
	v_exp_f32_e32 v183, v183
	v_mul_f32_e32 v202, s5, v202
	v_rcp_f32_e32 v182, v182
	v_add_f32_e32 v183, 1.0, v183
	v_mul_f32_e32 v203, v109, v168
	v_exp_f32_e32 v202, v202
	v_mul_f32_e32 v203, s5, v203
	v_rcp_f32_e32 v183, v183
	v_add_f32_e32 v202, 1.0, v202
	s_nop 0
	v_cvt_pk_bf16_f32 v184, v176, v177
	v_cvt_pk_bf16_f32 v185, v178, v179
	v_cvt_pk_bf16_f32 v186, v180, v181
	v_cvt_pk_bf16_f32 v187, v182, v183
	global_store_dwordx4 v[134:135], v[184:187], off
	v_lshl_add_u64 v[134:135], v[134:135], 0, s[6:7]
	v_mul_f32_e32 v204, v110, v168
	v_exp_f32_e32 v203, v203
	v_mul_f32_e32 v204, s5, v204
	v_rcp_f32_e32 v202, v202
	v_add_f32_e32 v203, 1.0, v203
	v_mul_f32_e32 v205, v111, v168
	v_exp_f32_e32 v204, v204
	v_mul_f32_e32 v205, s5, v205
	v_rcp_f32_e32 v203, v203
	v_add_f32_e32 v204, 1.0, v204
	v_mul_f32_e32 v206, v104, v168
	v_exp_f32_e32 v205, v205
	v_mul_f32_e32 v206, s5, v206
	v_rcp_f32_e32 v204, v204
	v_add_f32_e32 v205, 1.0, v205
	v_mul_f32_e32 v207, v105, v168
	v_exp_f32_e32 v206, v206
	v_mul_f32_e32 v207, s5, v207
	v_rcp_f32_e32 v205, v205
	v_add_f32_e32 v206, 1.0, v206
	v_mul_f32_e32 v208, v106, v168
	v_exp_f32_e32 v207, v207
	v_mul_f32_e32 v208, s5, v208
; DI u32x4 pack8(const float* x) { u32x4 v; v.x = cvt_pk(x[0], x[1]); v.y = cvt_pk(x[2], x[3]); v.z = cvt_pk(x[4], x[5]); v.w = cvt_pk(x[6], x[7]); return v; }
; DI float sigmoidf_(float v) { return __builtin_amdgcn_rcpf(1.0f + __expf(-v)); }
;     DI void operator()(const f32x4 (&acc)[2][2][4][2], const Unit& u, int wr, int wc, int fr, int fq) const {
;     ...
;             for (int ai = 0; ai < 2; ++ai)
; #pragma unroll
;                 for (int m = 0; m < 4; ++m) {
;                     float v[8];
; #pragma unroll
;                     for (int j = 0; j < 4; ++j) { v[j] = acc[ai][bj][m][0][j] * rstd[ai][m]; v[4 + j] = acc[ai][bj][m][1][j] * rstd[ai][m]; }
;                     if (act) {
; #pragma unroll
;                         for (int j = 0; j < 8; ++j) { const float sg = sigmoidf_(v[j]); v[j] = act == 1 ? v[j] * sg : sg; }
;                     }
;                     *(u32x4*)(O + (size_t)(row0 + ai * HALF + m * 16) * LDP + col0 + bj * HALF) = pack8(v);
;                 }
	v_rcp_f32_e32 v206, v206
	v_add_f32_e32 v207, 1.0, v207
	v_mul_f32_e32 v209, v107, v168
	v_exp_f32_e32 v208, v208
	v_mul_f32_e32 v209, s5, v209
	v_rcp_f32_e32 v207, v207
	v_add_f32_e32 v208, 1.0, v208
	v_mul_f32_e32 v176, v92, v166
	v_exp_f32_e32 v209, v209
	v_mul_f32_e32 v176, s5, v176
	v_rcp_f32_e32 v208, v208
	v_add_f32_e32 v209, 1.0, v209
	v_mul_f32_e32 v177, v93, v166
	v_exp_f32_e32 v176, v176
	v_mul_f32_e32 v177, s5, v177
	v_rcp_f32_e32 v209, v209
	v_add_f32_e32 v176, 1.0, v176
	s_nop 0
	v_cvt_pk_bf16_f32 v228, v202, v203
	v_cvt_pk_bf16_f32 v229, v204, v205
	v_cvt_pk_bf16_f32 v230, v206, v207
	v_cvt_pk_bf16_f32 v231, v208, v209
	global_store_dwordx4 v[134:135], v[228:231], off
	v_lshl_add_u64 v[134:135], v[134:135], 0, s[6:7]
	v_mul_f32_e32 v178, v94, v166
	v_exp_f32_e32 v177, v177
	v_mul_f32_e32 v178, s5, v178
	v_rcp_f32_e32 v176, v176
	v_add_f32_e32 v177, 1.0, v177
	v_mul_f32_e32 v179, v95, v166
	v_exp_f32_e32 v178, v178
	v_mul_f32_e32 v179, s5, v179
	v_rcp_f32_e32 v177, v177
	v_add_f32_e32 v178, 1.0, v178
	v_mul_f32_e32 v180, v88, v166
	v_exp_f32_e32 v179, v179
	v_mul_f32_e32 v180, s5, v180
	v_rcp_f32_e32 v178, v178
	v_add_f32_e32 v179, 1.0, v179
	v_mul_f32_e32 v181, v89, v166
	v_exp_f32_e32 v180, v180
	v_mul_f32_e32 v181, s5, v181
	v_rcp_f32_e32 v179, v179
	v_add_f32_e32 v180, 1.0, v180
	v_mul_f32_e32 v182, v90, v166
	v_exp_f32_e32 v181, v181
	v_mul_f32_e32 v182, s5, v182
	v_rcp_f32_e32 v180, v180
	v_add_f32_e32 v181, 1.0, v181
	v_mul_f32_e32 v183, v91, v166
	v_exp_f32_e32 v182, v182
	v_mul_f32_e32 v183, s5, v183
	v_rcp_f32_e32 v181, v181
	v_add_f32_e32 v182, 1.0, v182
	v_mul_f32_e32 v202, v76, v164
	v_exp_f32_e32 v183, v183
	v_mul_f32_e32 v202, s5, v202
	v_rcp_f32_e32 v182, v182
	v_add_f32_e32 v183, 1.0, v183
	v_mul_f32_e32 v203, v77, v164
	v_exp_f32_e32 v202, v202
	v_mul_f32_e32 v203, s5, v203
	v_rcp_f32_e32 v183, v183
	v_add_f32_e32 v202, 1.0, v202
	s_nop 0
	v_cvt_pk_bf16_f32 v184, v176, v177
	v_cvt_pk_bf16_f32 v185, v178, v179
	v_cvt_pk_bf16_f32 v186, v180, v181
	v_cvt_pk_bf16_f32 v187, v182, v183
	global_store_dwordx4 v[134:135], v[184:187], off
	v_lshl_add_u64 v[134:135], v[134:135], 0, s[6:7]
	v_mul_f32_e32 v204, v78, v164
	v_exp_f32_e32 v203, v203
	v_mul_f32_e32 v204, s5, v204
	v_rcp_f32_e32 v202, v202
	v_add_f32_e32 v203, 1.0, v203
	v_mul_f32_e32 v205, v79, v164
	v_exp_f32_e32 v204, v204
	v_mul_f32_e32 v205, s5, v205
	v_rcp_f32_e32 v203, v203
	v_add_f32_e32 v204, 1.0, v204
	v_mul_f32_e32 v206, v72, v164
	v_exp_f32_e32 v205, v205
	v_mul_f32_e32 v206, s5, v206
	v_rcp_f32_e32 v204, v204
	v_add_f32_e32 v205, 1.0, v205
	v_mul_f32_e32 v207, v73, v164
	v_exp_f32_e32 v206, v206
	v_mul_f32_e32 v207, s5, v207
	v_rcp_f32_e32 v205, v205
	v_add_f32_e32 v206, 1.0, v206
	v_mul_f32_e32 v208, v74, v164
	v_exp_f32_e32 v207, v207
	v_mul_f32_e32 v208, s5, v208
	v_rcp_f32_e32 v206, v206
	v_add_f32_e32 v207, 1.0, v207
	v_mul_f32_e32 v209, v75, v164
	v_exp_f32_e32 v208, v208
	v_mul_f32_e32 v209, s5, v209
	v_rcp_f32_e32 v207, v207
	v_add_f32_e32 v208, 1.0, v208
	v_mul_f32_e32 v176, v60, v162
	v_exp_f32_e32 v209, v209
	v_mul_f32_e32 v176, s5, v176
	v_rcp_f32_e32 v208, v208
	v_add_f32_e32 v209, 1.0, v209
	v_mul_f32_e32 v177, v61, v162
	v_exp_f32_e32 v176, v176
	v_mul_f32_e32 v177, s5, v177
	v_rcp_f32_e32 v209, v209
	v_add_f32_e32 v176, 1.0, v176
	s_nop 0
	v_cvt_pk_bf16_f32 v228, v202, v203
	v_cvt_pk_bf16_f32 v229, v204, v205
	v_cvt_pk_bf16_f32 v230, v206, v207
	v_cvt_pk_bf16_f32 v231, v208, v209
	global_store_dwordx4 v[134:135], v[228:231], off
	v_lshl_add_u64 v[134:135], v[134:135], 0, s[2:3]
	v_mul_f32_e32 v178, v62, v162
	v_exp_f32_e32 v177, v177
	v_mul_f32_e32 v178, s5, v178
	v_rcp_f32_e32 v176, v176
	v_add_f32_e32 v177, 1.0, v177
	v_mul_f32_e32 v179, v63, v162
	v_exp_f32_e32 v178, v178
	v_mul_f32_e32 v179, s5, v179
	v_rcp_f32_e32 v177, v177
	v_add_f32_e32 v178, 1.0, v178
	v_mul_f32_e32 v180, v56, v162
	v_exp_f32_e32 v179, v179
	v_mul_f32_e32 v180, s5, v180
	v_rcp_f32_e32 v178, v178
	v_add_f32_e32 v179, 1.0, v179
	v_mul_f32_e32 v181, v57, v162
	v_exp_f32_e32 v180, v180
	v_mul_f32_e32 v181, s5, v181
	v_rcp_f32_e32 v179, v179
	v_add_f32_e32 v180, 1.0, v180
	v_mul_f32_e32 v182, v58, v162
	v_exp_f32_e32 v181, v181
	v_mul_f32_e32 v182, s5, v182
	v_rcp_f32_e32 v180, v180
	v_add_f32_e32 v181, 1.0, v181
	v_mul_f32_e32 v183, v59, v162
	v_exp_f32_e32 v182, v182
	v_mul_f32_e32 v183, s5, v183
	v_rcp_f32_e32 v181, v181
	v_add_f32_e32 v182, 1.0, v182
	v_mul_f32_e32 v202, v44, v160
	v_exp_f32_e32 v183, v183
; DI u32x4 pack8(const float* x) { u32x4 v; v.x = cvt_pk(x[0], x[1]); v.y = cvt_pk(x[2], x[3]); v.z = cvt_pk(x[4], x[5]); v.w = cvt_pk(x[6], x[7]); return v; }
; DI float sigmoidf_(float v) { return __builtin_amdgcn_rcpf(1.0f + __expf(-v)); }
;     DI void operator()(const f32x4 (&acc)[2][2][4][2], const Unit& u, int wr, int wc, int fr, int fq) const {
;     ...
;             for (int ai = 0; ai < 2; ++ai)
; #pragma unroll
;                 for (int m = 0; m < 4; ++m) {
;                     float v[8];
; #pragma unroll
;                     for (int j = 0; j < 4; ++j) { v[j] = acc[ai][bj][m][0][j] * rstd[ai][m]; v[4 + j] = acc[ai][bj][m][1][j] * rstd[ai][m]; }
;                     if (act) {
; #pragma unroll
;                         for (int j = 0; j < 8; ++j) { const float sg = sigmoidf_(v[j]); v[j] = act == 1 ? v[j] * sg : sg; }
;                     }
;                     *(u32x4*)(O + (size_t)(row0 + ai * HALF + m * 16) * LDP + col0 + bj * HALF) = pack8(v);
;                 }
	v_mul_f32_e32 v202, s5, v202
	v_rcp_f32_e32 v182, v182
	v_add_f32_e32 v183, 1.0, v183
	v_mul_f32_e32 v203, v45, v160
	v_exp_f32_e32 v202, v202
	v_mul_f32_e32 v203, s5, v203
	v_rcp_f32_e32 v183, v183
	v_add_f32_e32 v202, 1.0, v202
	s_nop 0
	v_cvt_pk_bf16_f32 v184, v176, v177
	v_cvt_pk_bf16_f32 v185, v178, v179
	v_cvt_pk_bf16_f32 v186, v180, v181
	v_cvt_pk_bf16_f32 v187, v182, v183
	global_store_dwordx4 v[134:135], v[184:187], off
	v_lshl_add_u64 v[134:135], v[134:135], 0, s[6:7]
	v_mul_f32_e32 v204, v46, v160
	v_exp_f32_e32 v203, v203
	v_mul_f32_e32 v204, s5, v204
	v_rcp_f32_e32 v202, v202
	v_add_f32_e32 v203, 1.0, v203
	v_mul_f32_e32 v205, v47, v160
	v_exp_f32_e32 v204, v204
	v_mul_f32_e32 v205, s5, v205
	v_rcp_f32_e32 v203, v203
	v_add_f32_e32 v204, 1.0, v204
	v_mul_f32_e32 v206, v40, v160
	v_exp_f32_e32 v205, v205
	v_mul_f32_e32 v206, s5, v206
	v_rcp_f32_e32 v204, v204
	v_add_f32_e32 v205, 1.0, v205
	v_mul_f32_e32 v207, v41, v160
	v_exp_f32_e32 v206, v206
	v_mul_f32_e32 v207, s5, v207
	v_rcp_f32_e32 v205, v205
	v_add_f32_e32 v206, 1.0, v206
	v_mul_f32_e32 v208, v42, v160
	v_exp_f32_e32 v207, v207
	v_mul_f32_e32 v208, s5, v208
	v_rcp_f32_e32 v206, v206
	v_add_f32_e32 v207, 1.0, v207
	v_mul_f32_e32 v209, v43, v160
	v_exp_f32_e32 v208, v208
	v_mul_f32_e32 v209, s5, v209
	v_rcp_f32_e32 v207, v207
	v_add_f32_e32 v208, 1.0, v208
	v_mul_f32_e32 v176, v28, v158
	v_exp_f32_e32 v209, v209
	v_mul_f32_e32 v176, s5, v176
	v_rcp_f32_e32 v208, v208
	v_add_f32_e32 v209, 1.0, v209
	v_mul_f32_e32 v177, v29, v158
	v_exp_f32_e32 v176, v176
	v_mul_f32_e32 v177, s5, v177
	v_rcp_f32_e32 v209, v209
	v_add_f32_e32 v176, 1.0, v176
	s_nop 0
	v_cvt_pk_bf16_f32 v228, v202, v203
	v_cvt_pk_bf16_f32 v229, v204, v205
	v_cvt_pk_bf16_f32 v230, v206, v207
	v_cvt_pk_bf16_f32 v231, v208, v209
	global_store_dwordx4 v[134:135], v[228:231], off
	v_lshl_add_u64 v[134:135], v[134:135], 0, s[6:7]
	v_mul_f32_e32 v178, v30, v158
	v_exp_f32_e32 v177, v177
	v_mul_f32_e32 v178, s5, v178
	v_rcp_f32_e32 v176, v176
	v_add_f32_e32 v177, 1.0, v177
	v_mul_f32_e32 v179, v31, v158
	v_exp_f32_e32 v178, v178
	v_mul_f32_e32 v179, s5, v179
	v_rcp_f32_e32 v177, v177
	v_add_f32_e32 v178, 1.0, v178
	v_mul_f32_e32 v180, v24, v158
	v_exp_f32_e32 v179, v179
	v_mul_f32_e32 v180, s5, v180
	v_rcp_f32_e32 v178, v178
	v_add_f32_e32 v179, 1.0, v179
	v_mul_f32_e32 v181, v25, v158
	v_exp_f32_e32 v180, v180
	v_mul_f32_e32 v181, s5, v181
	v_rcp_f32_e32 v179, v179
	v_add_f32_e32 v180, 1.0, v180
	v_mul_f32_e32 v182, v26, v158
	v_exp_f32_e32 v181, v181
	v_mul_f32_e32 v182, s5, v182
	v_rcp_f32_e32 v180, v180
	v_add_f32_e32 v181, 1.0, v181
	v_mul_f32_e32 v183, v27, v158
	v_exp_f32_e32 v182, v182
	v_mul_f32_e32 v183, s5, v183
	v_rcp_f32_e32 v181, v181
	v_add_f32_e32 v182, 1.0, v182
	v_mul_f32_e32 v202, v12, v156
	v_exp_f32_e32 v183, v183
	v_mul_f32_e32 v202, s5, v202
	v_rcp_f32_e32 v182, v182
	v_add_f32_e32 v183, 1.0, v183
	v_mul_f32_e32 v203, v13, v156
	v_exp_f32_e32 v202, v202
	v_mul_f32_e32 v203, s5, v203
	v_rcp_f32_e32 v183, v183
	v_add_f32_e32 v202, 1.0, v202
	s_nop 0
	v_cvt_pk_bf16_f32 v184, v176, v177
	v_cvt_pk_bf16_f32 v185, v178, v179
	v_cvt_pk_bf16_f32 v186, v180, v181
	v_cvt_pk_bf16_f32 v187, v182, v183
	global_store_dwordx4 v[134:135], v[184:187], off
	v_lshl_add_u64 v[134:135], v[134:135], 0, s[6:7]
	v_mul_f32_e32 v204, v14, v156
	v_exp_f32_e32 v203, v203
	v_mul_f32_e32 v204, s5, v204
	v_rcp_f32_e32 v202, v202
	v_add_f32_e32 v203, 1.0, v203
	v_mul_f32_e32 v205, v15, v156
	v_exp_f32_e32 v204, v204
	v_mul_f32_e32 v205, s5, v205
	v_rcp_f32_e32 v203, v203
	v_add_f32_e32 v204, 1.0, v204
	v_mul_f32_e32 v206, v8, v156
	v_exp_f32_e32 v205, v205
	v_mul_f32_e32 v206, s5, v206
	v_rcp_f32_e32 v204, v204
	v_add_f32_e32 v205, 1.0, v205
	v_mul_f32_e32 v207, v9, v156
	v_exp_f32_e32 v206, v206
	v_mul_f32_e32 v207, s5, v207
	v_rcp_f32_e32 v205, v205
	v_add_f32_e32 v206, 1.0, v206
	v_mul_f32_e32 v208, v10, v156
	v_exp_f32_e32 v207, v207
	v_mul_f32_e32 v208, s5, v208
	v_rcp_f32_e32 v206, v206
	v_add_f32_e32 v207, 1.0, v207
	v_mul_f32_e32 v209, v11, v156
	v_exp_f32_e32 v208, v208
	v_mul_f32_e32 v209, s5, v209
	v_rcp_f32_e32 v207, v207
	v_add_f32_e32 v208, 1.0, v208
	v_exp_f32_e32 v209, v209
	v_rcp_f32_e32 v208, v208
	v_add_f32_e32 v209, 1.0, v209
	v_rcp_f32_e32 v209, v209
	s_nop 0
	v_cvt_pk_bf16_f32 v228, v202, v203
	v_cvt_pk_bf16_f32 v229, v204, v205
	v_cvt_pk_bf16_f32 v230, v206, v207
	v_cvt_pk_bf16_f32 v231, v208, v209
	global_store_dwordx4 v[134:135], v[228:231], off
	s_branch .Lp2e_b0_done
